# diff attn: near-window sub-blocks use the same hand-scheduled QK/exp/PV pipeline (bias-initialised accumulators)
# speedup vs baseline: 1.0308x; 1.0012x over previous
; #define LAS __attribute__((address_space(3)))
; #define MFMA32(a, b, c) __builtin_amdgcn_mfma_f32_32x32x16_bf16((a), (b), (c), 0, 0, 0)
; __device__ __forceinline__ s16x4 vtr(const LAS unsigned char* p) { return __builtin_bit_cast(s16x4, __builtin_amdgcn_ds_read_tr16_b64_v4i16((LAS v4i16_t*)p)); }
; __device__ __forceinline__ int crow(int r, int hi) { return (r & 3) + 8 * (r >> 2) + 4 * hi; }
; template <int MODE>
; __device__ __forceinline__ void attn_item(const AttnP& p, int b, int h, int qb, LAS unsigned char* lds) {
;     ...
;                     if (MODE == 0) {
;                         const LAS float* tab = (const LAS float*)(lds + TAB_OFF);
;                         if (qw - (kp0 + 31) >= 128) {
;                             const float cb = tab[255] - mfix;
; #pragma unroll
;                             for (int c = 0; c < NC; ++c) { ATT_QK(c, cb); ATT_TAIL(c); }
;                         } else {
;                             float binit[16];
; #pragma unroll
;                             for (int i = 0; i < 16; ++i) {
;                                 const int dist = qrow - (kp0 + crow(i, hh));
;                                 binit[i] = (dist < 0) ? -3e38f : (tab[dist > 255 ? 255 : dist] - mfix);
;                             }
; #pragma unroll
;                             for (int c = 0; c < NC; ++c) { ATT_QK(c, binit[i]); ATT_TAIL(c); }
;                         }
;     ...
; #pragma unroll
;                 for (int t2 = 0; t2 < 2; ++t2)
; #pragma unroll
;                     for (int d = 0; d < DV / 32; ++d) {
;                         const LAS unsigned char* vp = vtb + ((32 * kb2 + 16 * t2 + 4 * hh + ((lane & 15) >> 2)) * VPT + d * 32 + 16 * ((lane >> 4) & 1) + 4 * (lane & 3)) * 2;
;                         const s16x4 lo = vtr(vp), hi = vtr(vp + 8 * VPT * 2);
;                         const bf16x8 va = __builtin_shufflevector(lo, hi, 0, 1, 2, 3, 4, 5, 6, 7);
; #pragma unroll
;                         for (int c = 0; c < NC; ++c) O[c][d] = MFMA32(va, pb[c][t2], O[c][d]);
;                     }
.LBB0_501:
	s_cmpk_lt_i32 s11, 0x80
	s_mov_b64 s[2:3], -1
	s_cbranch_scc0 .Lfar_tile
	v_add_u32_e32 v243, v242, v235
	ds_read_b128 v[244:247], v243 offset:8704
	ds_read_b128 v[248:251], v243 offset:8736
	ds_read_b128 v[194:197], v243 offset:8768
	ds_read_b128 v[198:201], v243 offset:8800
	ds_read_b128 v[202:205], v243 offset:8832
	ds_read_b128 v[214:217], v207 offset:4096
	v_add_u32_e32 v218, s15, v238
	v_add_u32_e32 v219, s15, v239
	v_add_u32_e32 v146, s11, v236
	v_mov_b32_e32 v148, 0xff61b1e6
	v_add_u32_e32 v149, 31, v146
	s_mov_b32 s2, 0x12a10
	v_lshl_add_u32 v147, v146, 2, s2
	ds_read2_b32 v[130:131], v147 offset0:27 offset1:26
	ds_read2_b32 v[132:133], v147 offset0:25 offset1:24
	ds_read2_b32 v[134:135], v147 offset0:19 offset1:18
	ds_read2_b32 v[136:137], v147 offset0:17 offset1:16
	ds_read2_b32 v[138:139], v147 offset0:11 offset1:10
	ds_read2_b32 v[140:141], v147 offset0:9 offset1:8
	ds_read2_b32 v[142:143], v147 offset0:3 offset1:2
	ds_read2_b32 v[144:145], v147 offset0:1 offset1:0
	s_waitcnt lgkmcnt(0)
	v_cmp_le_i32_e64 vcc, 0, v149
	v_sub_f32_e32 v130, v130, v241
	v_cmp_le_i32_e64 s[2:3], 1, v149
	v_sub_f32_e32 v131, v131, v241
	v_cndmask_b32_e64 v130, v148, v130, vcc
	v_cmp_le_i32_e64 vcc, 2, v149
	v_sub_f32_e32 v132, v132, v241
	v_cndmask_b32_e64 v131, v148, v131, s[2:3]
	v_cmp_le_i32_e64 s[2:3], 3, v149
	v_sub_f32_e32 v133, v133, v241
	v_cndmask_b32_e64 v132, v148, v132, vcc
	v_cmp_le_i32_e64 vcc, 8, v149
	v_sub_f32_e32 v134, v134, v241
	v_cndmask_b32_e64 v133, v148, v133, s[2:3]
	v_cmp_le_i32_e64 s[2:3], 9, v149
	v_sub_f32_e32 v135, v135, v241
	v_cndmask_b32_e64 v134, v148, v134, vcc
	v_cmp_le_i32_e64 vcc, 10, v149
	v_sub_f32_e32 v136, v136, v241
	v_cndmask_b32_e64 v135, v148, v135, s[2:3]
	v_cmp_le_i32_e64 s[2:3], 11, v149
	v_sub_f32_e32 v137, v137, v241
	v_cndmask_b32_e64 v136, v148, v136, vcc
	v_cmp_le_i32_e64 vcc, 16, v149
	v_sub_f32_e32 v138, v138, v241
	v_cndmask_b32_e64 v137, v148, v137, s[2:3]
	v_cmp_le_i32_e64 s[2:3], 17, v149
	v_sub_f32_e32 v139, v139, v241
	v_cndmask_b32_e64 v138, v148, v138, vcc
	v_cmp_le_i32_e64 vcc, 18, v149
	v_sub_f32_e32 v140, v140, v241
	v_cndmask_b32_e64 v139, v148, v139, s[2:3]
	v_cmp_le_i32_e64 s[2:3], 19, v149
	v_sub_f32_e32 v141, v141, v241
	v_cndmask_b32_e64 v140, v148, v140, vcc
	v_cmp_le_i32_e64 vcc, 24, v149
	v_sub_f32_e32 v142, v142, v241
	v_cndmask_b32_e64 v141, v148, v141, s[2:3]
	v_cmp_le_i32_e64 s[2:3], 25, v149
	v_sub_f32_e32 v143, v143, v241
	v_cndmask_b32_e64 v142, v148, v142, vcc
	v_cmp_le_i32_e64 vcc, 26, v149
	v_sub_f32_e32 v144, v144, v241
	v_cndmask_b32_e64 v143, v148, v143, s[2:3]
	v_cmp_le_i32_e64 s[2:3], 27, v149
	v_sub_f32_e32 v145, v145, v241
	s_nop 0
	v_cndmask_b32_e64 v144, v148, v144, vcc
	v_cndmask_b32_e64 v145, v148, v145, s[2:3]
	s_nop 1
	v_mfma_f32_32x32x16_bf16 v[146:161], v[244:247], v[162:165], v[130:145]
	v_mfma_f32_32x32x16_bf16 v[146:161], v[248:251], v[166:169], v[146:161]
	ds_read_b128 v[244:247], v243 offset:8864
	ds_read_b128 v[248:251], v207 offset:5120
	v_mfma_f32_32x32x16_bf16 v[146:161], v[194:197], v[170:173], v[146:161]
	v_mfma_f32_32x32x16_bf16 v[146:161], v[198:201], v[174:177], v[146:161]
	ds_read_b128 v[194:197], v243 offset:8896
	ds_read_b128 v[198:201], v207 offset:6144
	v_mfma_f32_32x32x16_bf16 v[130:145], v[202:205], v[214:217], v[130:145]
	ds_read_b128 v[202:205], v243 offset:8928
	ds_read_b128 v[214:217], v207 offset:7168
	s_waitcnt lgkmcnt(4)
	v_mfma_f32_32x32x16_bf16 v[130:145], v[244:247], v[248:251], v[130:145]
	ds_read_b64_tr_b16 v[244:245], v218 offset:17408
	ds_read_b64_tr_b16 v[246:247], v218 offset:19968
	ds_read_b64_tr_b16 v[248:249], v218 offset:17472
	ds_read_b64_tr_b16 v[250:251], v218 offset:20032
	s_nop 0
	v_exp_f32_e32 v146, v146
	v_exp_f32_e32 v147, v147
	v_exp_f32_e32 v148, v148
	v_add_f32_e32 v220, v146, v147
	v_exp_f32_e32 v149, v149
	v_add_f32_e32 v220, v148, v220
	v_exp_f32_e32 v150, v150
	s_waitcnt lgkmcnt(6)
	v_mfma_f32_32x32x16_bf16 v[130:145], v[194:197], v[198:201], v[130:145]
	ds_read_b64_tr_b16 v[194:195], v218 offset:17536
	ds_read_b64_tr_b16 v[196:197], v218 offset:20096
	ds_read_b64_tr_b16 v[198:199], v218 offset:17600
	ds_read_b64_tr_b16 v[200:201], v218 offset:20160
	v_add_f32_e32 v220, v149, v220
	v_exp_f32_e32 v151, v151
	v_add_f32_e32 v220, v150, v220
	v_exp_f32_e32 v152, v152
	v_add_f32_e32 v220, v151, v220
	v_exp_f32_e32 v153, v153
	s_waitcnt lgkmcnt(8)
	v_mfma_f32_32x32x16_bf16 v[130:145], v[202:205], v[214:217], v[130:145]
	ds_read_b64_tr_b16 v[202:203], v219 offset:17408
	ds_read_b64_tr_b16 v[204:205], v219 offset:19968
	ds_read_b64_tr_b16 v[214:215], v219 offset:17472
	ds_read_b64_tr_b16 v[216:217], v219 offset:20032
	v_add_f32_e32 v220, v152, v220
	v_cvt_pk_bf16_f32 v146, v146, v147
	v_add_f32_e32 v220, v153, v220
	v_cvt_pk_bf16_f32 v147, v148, v149
	v_cvt_pk_bf16_f32 v148, v150, v151
	v_cvt_pk_bf16_f32 v149, v152, v153
	s_nop 1
	s_waitcnt lgkmcnt(10)
	v_mfma_f32_32x32x16_bf16 v[114:129], v[244:247], v[146:149], v[114:129]
	v_exp_f32_e32 v154, v154
	v_exp_f32_e32 v155, v155
	v_add_f32_e32 v220, v154, v220
	v_exp_f32_e32 v156, v156
	v_add_f32_e32 v220, v155, v220
	v_exp_f32_e32 v157, v157
	s_waitcnt lgkmcnt(8)
	v_mfma_f32_32x32x16_bf16 v[82:97], v[248:251], v[146:149], v[82:97]
	v_add_f32_e32 v220, v156, v220
	v_exp_f32_e32 v158, v158
	v_add_f32_e32 v220, v157, v220
	v_exp_f32_e32 v159, v159
	v_add_f32_e32 v220, v158, v220
	s_waitcnt lgkmcnt(6)
	v_mfma_f32_32x32x16_bf16 v[50:65], v[194:197], v[146:149], v[50:65]
	v_exp_f32_e32 v160, v160
	v_add_f32_e32 v220, v159, v220
	v_exp_f32_e32 v161, v161
	v_add_f32_e32 v220, v160, v220
	v_cvt_pk_bf16_f32 v150, v154, v155
	s_waitcnt lgkmcnt(4)
; #define LAS __attribute__((address_space(3)))
; #define MFMA32(a, b, c) __builtin_amdgcn_mfma_f32_32x32x16_bf16((a), (b), (c), 0, 0, 0)
; __device__ __forceinline__ s16x4 vtr(const LAS unsigned char* p) { return __builtin_bit_cast(s16x4, __builtin_amdgcn_ds_read_tr16_b64_v4i16((LAS v4i16_t*)p)); }
; __device__ __forceinline__ int crow(int r, int hi) { return (r & 3) + 8 * (r >> 2) + 4 * hi; }
; template <int MODE>
; __device__ __forceinline__ void attn_item(const AttnP& p, int b, int h, int qb, LAS unsigned char* lds) {
;     ...
;                     if (MODE == 0) {
;                         const LAS float* tab = (const LAS float*)(lds + TAB_OFF);
;                         if (qw - (kp0 + 31) >= 128) {
;                             const float cb = tab[255] - mfix;
; #pragma unroll
;                             for (int c = 0; c < NC; ++c) { ATT_QK(c, cb); ATT_TAIL(c); }
;                         } else {
;                             float binit[16];
; #pragma unroll
;                             for (int i = 0; i < 16; ++i) {
;                                 const int dist = qrow - (kp0 + crow(i, hh));
;                                 binit[i] = (dist < 0) ? -3e38f : (tab[dist > 255 ? 255 : dist] - mfix);
;                             }
; #pragma unroll
;                             for (int c = 0; c < NC; ++c) { ATT_QK(c, binit[i]); ATT_TAIL(c); }
;                         }
;     ...
; #pragma unroll
;                 for (int t2 = 0; t2 < 2; ++t2)
; #pragma unroll
;                     for (int d = 0; d < DV / 32; ++d) {
;                         const LAS unsigned char* vp = vtb + ((32 * kb2 + 16 * t2 + 4 * hh + ((lane & 15) >> 2)) * VPT + d * 32 + 16 * ((lane >> 4) & 1) + 4 * (lane & 3)) * 2;
;                         const s16x4 lo = vtr(vp), hi = vtr(vp + 8 * VPT * 2);
;                         const bf16x8 va = __builtin_shufflevector(lo, hi, 0, 1, 2, 3, 4, 5, 6, 7);
; #pragma unroll
;                         for (int c = 0; c < NC; ++c) O[c][d] = MFMA32(va, pb[c][t2], O[c][d]);
;                     }
	v_mfma_f32_32x32x16_bf16 v[34:49], v[198:201], v[146:149], v[34:49]
	v_add_f32_e32 v220, v161, v220
	v_cvt_pk_bf16_f32 v151, v156, v157
	v_cvt_pk_bf16_f32 v152, v158, v159
	v_cvt_pk_bf16_f32 v153, v160, v161
	v_add_f32_e32 v209, v209, v220
	ds_read_b64_tr_b16 v[154:155], v219 offset:17536
	ds_read_b64_tr_b16 v[156:157], v219 offset:20096
	ds_read_b64_tr_b16 v[158:159], v219 offset:17600
	ds_read_b64_tr_b16 v[160:161], v219 offset:20160
	s_waitcnt lgkmcnt(6)
	v_mfma_f32_32x32x16_bf16 v[114:129], v[202:205], v[150:153], v[114:129]
	v_exp_f32_e32 v130, v130
	v_exp_f32_e32 v131, v131
	v_exp_f32_e32 v132, v132
	v_add_f32_e32 v213, v130, v131
	v_exp_f32_e32 v133, v133
	s_waitcnt lgkmcnt(4)
	v_mfma_f32_32x32x16_bf16 v[82:97], v[214:217], v[150:153], v[82:97]
	v_add_f32_e32 v213, v132, v213
	v_exp_f32_e32 v134, v134
	v_add_f32_e32 v213, v133, v213
	v_exp_f32_e32 v135, v135
	v_add_f32_e32 v213, v134, v213
	s_waitcnt lgkmcnt(2)
	v_mfma_f32_32x32x16_bf16 v[50:65], v[154:157], v[150:153], v[50:65]
	v_exp_f32_e32 v136, v136
	v_add_f32_e32 v213, v135, v213
	v_exp_f32_e32 v137, v137
	v_add_f32_e32 v213, v136, v213
	v_cvt_pk_bf16_f32 v130, v130, v131
	s_waitcnt lgkmcnt(0)
	v_mfma_f32_32x32x16_bf16 v[34:49], v[158:161], v[150:153], v[34:49]
	v_add_f32_e32 v213, v137, v213
	v_cvt_pk_bf16_f32 v131, v132, v133
	v_cvt_pk_bf16_f32 v132, v134, v135
	v_cvt_pk_bf16_f32 v133, v136, v137
	s_nop 1
	v_mfma_f32_32x32x16_bf16 v[98:113], v[244:247], v[130:133], v[98:113]
	v_exp_f32_e32 v138, v138
	v_exp_f32_e32 v139, v139
	v_add_f32_e32 v213, v138, v213
	v_exp_f32_e32 v140, v140
	v_add_f32_e32 v213, v139, v213
	v_exp_f32_e32 v141, v141
	v_mfma_f32_32x32x16_bf16 v[66:81], v[248:251], v[130:133], v[66:81]
	v_add_f32_e32 v213, v140, v213
	v_exp_f32_e32 v142, v142
	v_add_f32_e32 v213, v141, v213
	v_exp_f32_e32 v143, v143
	v_add_f32_e32 v213, v142, v213
	v_mfma_f32_32x32x16_bf16 v[18:33], v[194:197], v[130:133], v[18:33]
	v_exp_f32_e32 v144, v144
	v_add_f32_e32 v213, v143, v213
	v_exp_f32_e32 v145, v145
	v_add_f32_e32 v213, v144, v213
	v_cvt_pk_bf16_f32 v134, v138, v139
	v_mfma_f32_32x32x16_bf16 v[2:17], v[198:201], v[130:133], v[2:17]
	v_add_f32_e32 v213, v145, v213
	v_cvt_pk_bf16_f32 v135, v140, v141
	v_cvt_pk_bf16_f32 v136, v142, v143
	v_cvt_pk_bf16_f32 v137, v144, v145
	v_add_f32_e32 v208, v208, v213
	s_nop 1
	v_mfma_f32_32x32x16_bf16 v[98:113], v[202:205], v[134:137], v[98:113]
	v_mfma_f32_32x32x16_bf16 v[66:81], v[214:217], v[134:137], v[66:81]
	v_mfma_f32_32x32x16_bf16 v[18:33], v[154:157], v[134:137], v[18:33]
	v_mfma_f32_32x32x16_bf16 v[2:17], v[158:161], v[134:137], v[2:17]
	s_add_i32 s2, s14, 64
	s_cmp_gt_i32 s2, s1
	s_cbranch_scc1 .LBB0_500
.LBB0_538:
	s_add_i32 s2, s11, 32
	s_cmpk_gt_i32 s2, 0x7f
	s_cbranch_scc1 .Lsb_far0
	v_add_u32_e32 v243, v242, v235
	ds_read_b128 v[244:247], v243 offset:0
	ds_read_b128 v[248:251], v243 offset:32
	ds_read_b128 v[194:197], v243 offset:64
	ds_read_b128 v[198:201], v243 offset:96
	ds_read_b128 v[202:205], v243 offset:128
	ds_read_b128 v[214:217], v207 offset:4096
	v_add_u32_e32 v218, s15, v237
	v_add_u32_e32 v219, s15, v240
	v_add_u32_e32 v146, s11, v236
	v_mov_b32_e32 v148, 0xff61b1e6
	v_add_u32_e32 v149, 63, v146
	s_mov_b32 s2, 0x12a90
	v_lshl_add_u32 v147, v146, 2, s2
	ds_read2_b32 v[130:131], v147 offset0:27 offset1:26
	ds_read2_b32 v[132:133], v147 offset0:25 offset1:24
	ds_read2_b32 v[134:135], v147 offset0:19 offset1:18
	ds_read2_b32 v[136:137], v147 offset0:17 offset1:16
	ds_read2_b32 v[138:139], v147 offset0:11 offset1:10
	ds_read2_b32 v[140:141], v147 offset0:9 offset1:8
	ds_read2_b32 v[142:143], v147 offset0:3 offset1:2
	ds_read2_b32 v[144:145], v147 offset0:1 offset1:0
	s_waitcnt lgkmcnt(0)
	v_cmp_le_i32_e64 vcc, 0, v149
	v_sub_f32_e32 v130, v130, v241
	v_cmp_le_i32_e64 s[2:3], 1, v149
	v_sub_f32_e32 v131, v131, v241
	v_cndmask_b32_e64 v130, v148, v130, vcc
	v_cmp_le_i32_e64 vcc, 2, v149
	v_sub_f32_e32 v132, v132, v241
	v_cndmask_b32_e64 v131, v148, v131, s[2:3]
	v_cmp_le_i32_e64 s[2:3], 3, v149
	v_sub_f32_e32 v133, v133, v241
	v_cndmask_b32_e64 v132, v148, v132, vcc
	v_cmp_le_i32_e64 vcc, 8, v149
	v_sub_f32_e32 v134, v134, v241
	v_cndmask_b32_e64 v133, v148, v133, s[2:3]
	v_cmp_le_i32_e64 s[2:3], 9, v149
	v_sub_f32_e32 v135, v135, v241
	v_cndmask_b32_e64 v134, v148, v134, vcc
	v_cmp_le_i32_e64 vcc, 10, v149
	v_sub_f32_e32 v136, v136, v241
	v_cndmask_b32_e64 v135, v148, v135, s[2:3]
	v_cmp_le_i32_e64 s[2:3], 11, v149
	v_sub_f32_e32 v137, v137, v241
	v_cndmask_b32_e64 v136, v148, v136, vcc
	v_cmp_le_i32_e64 vcc, 16, v149
	v_sub_f32_e32 v138, v138, v241
	v_cndmask_b32_e64 v137, v148, v137, s[2:3]
	v_cmp_le_i32_e64 s[2:3], 17, v149
	v_sub_f32_e32 v139, v139, v241
	v_cndmask_b32_e64 v138, v148, v138, vcc
	v_cmp_le_i32_e64 vcc, 18, v149
	v_sub_f32_e32 v140, v140, v241
	v_cndmask_b32_e64 v139, v148, v139, s[2:3]
	v_cmp_le_i32_e64 s[2:3], 19, v149
	v_sub_f32_e32 v141, v141, v241
	v_cndmask_b32_e64 v140, v148, v140, vcc
	v_cmp_le_i32_e64 vcc, 24, v149
	v_sub_f32_e32 v142, v142, v241
	v_cndmask_b32_e64 v141, v148, v141, s[2:3]
	v_cmp_le_i32_e64 s[2:3], 25, v149
	v_sub_f32_e32 v143, v143, v241
	v_cndmask_b32_e64 v142, v148, v142, vcc
	v_cmp_le_i32_e64 vcc, 26, v149
	v_sub_f32_e32 v144, v144, v241
	v_cndmask_b32_e64 v143, v148, v143, s[2:3]
	v_cmp_le_i32_e64 s[2:3], 27, v149
	v_sub_f32_e32 v145, v145, v241
	s_nop 0
	v_cndmask_b32_e64 v144, v148, v144, vcc
	v_cndmask_b32_e64 v145, v148, v145, s[2:3]
	s_nop 1
	v_mfma_f32_32x32x16_bf16 v[146:161], v[244:247], v[162:165], v[130:145]
	v_mfma_f32_32x32x16_bf16 v[146:161], v[248:251], v[166:169], v[146:161]
	ds_read_b128 v[244:247], v243 offset:160
	ds_read_b128 v[248:251], v207 offset:5120
	v_mfma_f32_32x32x16_bf16 v[146:161], v[194:197], v[170:173], v[146:161]
	v_mfma_f32_32x32x16_bf16 v[146:161], v[198:201], v[174:177], v[146:161]
	ds_read_b128 v[194:197], v243 offset:192
	ds_read_b128 v[198:201], v207 offset:6144
	v_mfma_f32_32x32x16_bf16 v[130:145], v[202:205], v[214:217], v[130:145]
	ds_read_b128 v[202:205], v243 offset:224
	ds_read_b128 v[214:217], v207 offset:7168
	s_waitcnt lgkmcnt(4)
; #define LAS __attribute__((address_space(3)))
; #define MFMA32(a, b, c) __builtin_amdgcn_mfma_f32_32x32x16_bf16((a), (b), (c), 0, 0, 0)
; __device__ __forceinline__ s16x4 vtr(const LAS unsigned char* p) { return __builtin_bit_cast(s16x4, __builtin_amdgcn_ds_read_tr16_b64_v4i16((LAS v4i16_t*)p)); }
; template <int MODE>
; __device__ __forceinline__ void attn_item(const AttnP& p, int b, int h, int qb, LAS unsigned char* lds) {
;     ...
; #pragma unroll
;                 for (int t2 = 0; t2 < 2; ++t2)
; #pragma unroll
;                     for (int d = 0; d < DV / 32; ++d) {
;                         const LAS unsigned char* vp = vtb + ((32 * kb2 + 16 * t2 + 4 * hh + ((lane & 15) >> 2)) * VPT + d * 32 + 16 * ((lane >> 4) & 1) + 4 * (lane & 3)) * 2;
;                         const s16x4 lo = vtr(vp), hi = vtr(vp + 8 * VPT * 2);
;                         const bf16x8 va = __builtin_shufflevector(lo, hi, 0, 1, 2, 3, 4, 5, 6, 7);
; #pragma unroll
;                         for (int c = 0; c < NC; ++c) O[c][d] = MFMA32(va, pb[c][t2], O[c][d]);
;                     }
	v_mfma_f32_32x32x16_bf16 v[130:145], v[244:247], v[248:251], v[130:145]
	ds_read_b64_tr_b16 v[244:245], v218 offset:17408
	ds_read_b64_tr_b16 v[246:247], v218 offset:19968
	ds_read_b64_tr_b16 v[248:249], v218 offset:17472
	ds_read_b64_tr_b16 v[250:251], v218 offset:20032
	s_nop 0
	v_exp_f32_e32 v146, v146
	v_exp_f32_e32 v147, v147
	v_exp_f32_e32 v148, v148
	v_add_f32_e32 v220, v146, v147
	v_exp_f32_e32 v149, v149
	v_add_f32_e32 v220, v148, v220
	v_exp_f32_e32 v150, v150
	s_waitcnt lgkmcnt(6)
	v_mfma_f32_32x32x16_bf16 v[130:145], v[194:197], v[198:201], v[130:145]
	ds_read_b64_tr_b16 v[194:195], v218 offset:17536
	ds_read_b64_tr_b16 v[196:197], v218 offset:20096
	ds_read_b64_tr_b16 v[198:199], v218 offset:17600
	ds_read_b64_tr_b16 v[200:201], v218 offset:20160
	v_add_f32_e32 v220, v149, v220
	v_exp_f32_e32 v151, v151
	v_add_f32_e32 v220, v150, v220
	v_exp_f32_e32 v152, v152
	v_add_f32_e32 v220, v151, v220
	v_exp_f32_e32 v153, v153
	s_waitcnt lgkmcnt(8)
	v_mfma_f32_32x32x16_bf16 v[130:145], v[202:205], v[214:217], v[130:145]
	ds_read_b64_tr_b16 v[202:203], v219 offset:17408
	ds_read_b64_tr_b16 v[204:205], v219 offset:19968
	ds_read_b64_tr_b16 v[214:215], v219 offset:17472
	ds_read_b64_tr_b16 v[216:217], v219 offset:20032
	v_add_f32_e32 v220, v152, v220
	v_cvt_pk_bf16_f32 v146, v146, v147
	v_add_f32_e32 v220, v153, v220
	v_cvt_pk_bf16_f32 v147, v148, v149
	v_cvt_pk_bf16_f32 v148, v150, v151
	v_cvt_pk_bf16_f32 v149, v152, v153
	s_nop 1
	s_waitcnt lgkmcnt(10)
	v_mfma_f32_32x32x16_bf16 v[114:129], v[244:247], v[146:149], v[114:129]
	v_exp_f32_e32 v154, v154
	v_exp_f32_e32 v155, v155
	v_add_f32_e32 v220, v154, v220
	v_exp_f32_e32 v156, v156
	v_add_f32_e32 v220, v155, v220
	v_exp_f32_e32 v157, v157
	s_waitcnt lgkmcnt(8)
	v_mfma_f32_32x32x16_bf16 v[82:97], v[248:251], v[146:149], v[82:97]
	v_add_f32_e32 v220, v156, v220
	v_exp_f32_e32 v158, v158
	v_add_f32_e32 v220, v157, v220
	v_exp_f32_e32 v159, v159
	v_add_f32_e32 v220, v158, v220
	s_waitcnt lgkmcnt(6)
	v_mfma_f32_32x32x16_bf16 v[50:65], v[194:197], v[146:149], v[50:65]
	v_exp_f32_e32 v160, v160
	v_add_f32_e32 v220, v159, v220
	v_exp_f32_e32 v161, v161
	v_add_f32_e32 v220, v160, v220
	v_cvt_pk_bf16_f32 v150, v154, v155
	s_waitcnt lgkmcnt(4)
	v_mfma_f32_32x32x16_bf16 v[34:49], v[198:201], v[146:149], v[34:49]
	v_add_f32_e32 v220, v161, v220
	v_cvt_pk_bf16_f32 v151, v156, v157
	v_cvt_pk_bf16_f32 v152, v158, v159
	v_cvt_pk_bf16_f32 v153, v160, v161
	v_add_f32_e32 v209, v209, v220
	ds_read_b64_tr_b16 v[154:155], v219 offset:17536
	ds_read_b64_tr_b16 v[156:157], v219 offset:20096
	ds_read_b64_tr_b16 v[158:159], v219 offset:17600
	ds_read_b64_tr_b16 v[160:161], v219 offset:20160
	s_waitcnt lgkmcnt(6)
	v_mfma_f32_32x32x16_bf16 v[114:129], v[202:205], v[150:153], v[114:129]
	v_exp_f32_e32 v130, v130
	v_exp_f32_e32 v131, v131
	v_exp_f32_e32 v132, v132
	v_add_f32_e32 v213, v130, v131
	v_exp_f32_e32 v133, v133
	s_waitcnt lgkmcnt(4)
	v_mfma_f32_32x32x16_bf16 v[82:97], v[214:217], v[150:153], v[82:97]
	v_add_f32_e32 v213, v132, v213
	v_exp_f32_e32 v134, v134
	v_add_f32_e32 v213, v133, v213
	v_exp_f32_e32 v135, v135
	v_add_f32_e32 v213, v134, v213
	s_waitcnt lgkmcnt(2)
	v_mfma_f32_32x32x16_bf16 v[50:65], v[154:157], v[150:153], v[50:65]
	v_exp_f32_e32 v136, v136
	v_add_f32_e32 v213, v135, v213
	v_exp_f32_e32 v137, v137
	v_add_f32_e32 v213, v136, v213
	v_cvt_pk_bf16_f32 v130, v130, v131
	s_waitcnt lgkmcnt(0)
	v_mfma_f32_32x32x16_bf16 v[34:49], v[158:161], v[150:153], v[34:49]
	v_add_f32_e32 v213, v137, v213
	v_cvt_pk_bf16_f32 v131, v132, v133
	v_cvt_pk_bf16_f32 v132, v134, v135
	v_cvt_pk_bf16_f32 v133, v136, v137
	s_nop 1
	v_mfma_f32_32x32x16_bf16 v[98:113], v[244:247], v[130:133], v[98:113]
	v_exp_f32_e32 v138, v138
	v_exp_f32_e32 v139, v139
	v_add_f32_e32 v213, v138, v213
	v_exp_f32_e32 v140, v140
	v_add_f32_e32 v213, v139, v213
	v_exp_f32_e32 v141, v141
	v_mfma_f32_32x32x16_bf16 v[66:81], v[248:251], v[130:133], v[66:81]
	v_add_f32_e32 v213, v140, v213
	v_exp_f32_e32 v142, v142
	v_add_f32_e32 v213, v141, v213
	v_exp_f32_e32 v143, v143
	v_add_f32_e32 v213, v142, v213
	v_mfma_f32_32x32x16_bf16 v[18:33], v[194:197], v[130:133], v[18:33]
	v_exp_f32_e32 v144, v144
	v_add_f32_e32 v213, v143, v213
	v_exp_f32_e32 v145, v145
	v_add_f32_e32 v213, v144, v213
	v_cvt_pk_bf16_f32 v134, v138, v139
	v_mfma_f32_32x32x16_bf16 v[2:17], v[198:201], v[130:133], v[2:17]
	v_add_f32_e32 v213, v145, v213
	v_cvt_pk_bf16_f32 v135, v140, v141
	v_cvt_pk_bf16_f32 v136, v142, v143
	v_cvt_pk_bf16_f32 v137, v144, v145
	v_add_f32_e32 v208, v208, v213
	s_nop 1
	v_mfma_f32_32x32x16_bf16 v[98:113], v[202:205], v[134:137], v[98:113]
	v_mfma_f32_32x32x16_bf16 v[66:81], v[214:217], v[134:137], v[66:81]
	v_mfma_f32_32x32x16_bf16 v[18:33], v[154:157], v[134:137], v[18:33]
	v_mfma_f32_32x32x16_bf16 v[2:17], v[158:161], v[134:137], v[2:17]
	s_branch .Lsb_end
; #define LAS __attribute__((address_space(3)))
; #define MFMA32(a, b, c) __builtin_amdgcn_mfma_f32_32x32x16_bf16((a), (b), (c), 0, 0, 0)
; __device__ __forceinline__ s16x4 vtr(const LAS unsigned char* p) { return __builtin_bit_cast(s16x4, __builtin_amdgcn_ds_read_tr16_b64_v4i16((LAS v4i16_t*)p)); }
; template <int MODE>
; __device__ __forceinline__ void attn_item(const AttnP& p, int b, int h, int qb, LAS unsigned char* lds) {
;     ...
;                         if (qw - (kp0 + 31) >= 128) {
;                             const float cb = tab[255] - mfix;
; #pragma unroll
;                             for (int c = 0; c < NC; ++c) { ATT_QK(c, cb); ATT_TAIL(c); }
;     ...
; #pragma unroll
;                 for (int t2 = 0; t2 < 2; ++t2)
; #pragma unroll
;                     for (int d = 0; d < DV / 32; ++d) {
;                         const LAS unsigned char* vp = vtb + ((32 * kb2 + 16 * t2 + 4 * hh + ((lane & 15) >> 2)) * VPT + d * 32 + 16 * ((lane >> 4) & 1) + 4 * (lane & 3)) * 2;
;                         const s16x4 lo = vtr(vp), hi = vtr(vp + 8 * VPT * 2);
;                         const bf16x8 va = __builtin_shufflevector(lo, hi, 0, 1, 2, 3, 4, 5, 6, 7);
; #pragma unroll
;                         for (int c = 0; c < NC; ++c) O[c][d] = MFMA32(va, pb[c][t2], O[c][d]);
;                     }
.Lsb_far0:
	v_add_u32_e32 v243, v242, v235
	ds_read_b128 v[244:247], v243 offset:0
	ds_read_b128 v[248:251], v243 offset:32
	ds_read_b128 v[194:197], v243 offset:64
	ds_read_b128 v[198:201], v243 offset:96
	ds_read_b128 v[202:205], v243 offset:128
	ds_read_b128 v[214:217], v207 offset:4096
	v_add_u32_e32 v218, s15, v237
	v_add_u32_e32 v219, s15, v240
	s_waitcnt lgkmcnt(5)
	v_mfma_f32_32x32x16_bf16 v[146:161], v[244:247], v[162:165], 0
	s_waitcnt lgkmcnt(4)
	v_mfma_f32_32x32x16_bf16 v[146:161], v[248:251], v[166:169], v[146:161]
	ds_read_b128 v[244:247], v243 offset:160
	ds_read_b128 v[248:251], v207 offset:5120
	s_waitcnt lgkmcnt(5)
	v_mfma_f32_32x32x16_bf16 v[146:161], v[194:197], v[170:173], v[146:161]
	s_waitcnt lgkmcnt(4)
	v_mfma_f32_32x32x16_bf16 v[146:161], v[198:201], v[174:177], v[146:161]
	ds_read_b128 v[194:197], v243 offset:192
	ds_read_b128 v[198:201], v207 offset:6144
	s_waitcnt lgkmcnt(4)
	v_mfma_f32_32x32x16_bf16 v[130:145], v[202:205], v[214:217], 0
	ds_read_b128 v[202:205], v243 offset:224
	ds_read_b128 v[214:217], v207 offset:7168
	s_waitcnt lgkmcnt(4)
	v_mfma_f32_32x32x16_bf16 v[130:145], v[244:247], v[248:251], v[130:145]
	ds_read_b64_tr_b16 v[244:245], v218 offset:17408
	ds_read_b64_tr_b16 v[246:247], v218 offset:19968
	ds_read_b64_tr_b16 v[248:249], v218 offset:17472
	ds_read_b64_tr_b16 v[250:251], v218 offset:20032
	v_exp_f32_e32 v146, v146
	v_exp_f32_e32 v147, v147
	v_exp_f32_e32 v148, v148
	v_add_f32_e32 v220, v146, v147
	v_exp_f32_e32 v149, v149
	v_add_f32_e32 v220, v148, v220
	v_exp_f32_e32 v150, v150
	s_waitcnt lgkmcnt(6)
	v_mfma_f32_32x32x16_bf16 v[130:145], v[194:197], v[198:201], v[130:145]
	ds_read_b64_tr_b16 v[194:195], v218 offset:17536
	ds_read_b64_tr_b16 v[196:197], v218 offset:20096
	ds_read_b64_tr_b16 v[198:199], v218 offset:17600
	ds_read_b64_tr_b16 v[200:201], v218 offset:20160
	v_add_f32_e32 v220, v149, v220
	v_exp_f32_e32 v151, v151
	v_add_f32_e32 v220, v150, v220
	v_exp_f32_e32 v152, v152
	v_add_f32_e32 v220, v151, v220
	v_exp_f32_e32 v153, v153
	s_waitcnt lgkmcnt(8)
	v_mfma_f32_32x32x16_bf16 v[130:145], v[202:205], v[214:217], v[130:145]
	ds_read_b64_tr_b16 v[202:203], v219 offset:17408
	ds_read_b64_tr_b16 v[204:205], v219 offset:19968
	ds_read_b64_tr_b16 v[214:215], v219 offset:17472
	ds_read_b64_tr_b16 v[216:217], v219 offset:20032
	v_add_f32_e32 v220, v152, v220
	v_cvt_pk_bf16_f32 v146, v146, v147
	v_add_f32_e32 v220, v153, v220
	v_cvt_pk_bf16_f32 v147, v148, v149
	v_cvt_pk_bf16_f32 v148, v150, v151
	v_cvt_pk_bf16_f32 v149, v152, v153
	s_nop 1
	s_waitcnt lgkmcnt(10)
	v_mfma_f32_32x32x16_bf16 v[114:129], v[244:247], v[146:149], v[114:129]
	v_exp_f32_e32 v154, v154
	v_exp_f32_e32 v155, v155
	v_add_f32_e32 v220, v154, v220
	v_exp_f32_e32 v156, v156
	v_add_f32_e32 v220, v155, v220
	v_exp_f32_e32 v157, v157
	s_waitcnt lgkmcnt(8)
	v_mfma_f32_32x32x16_bf16 v[82:97], v[248:251], v[146:149], v[82:97]
	v_add_f32_e32 v220, v156, v220
	v_exp_f32_e32 v158, v158
	v_add_f32_e32 v220, v157, v220
	v_exp_f32_e32 v159, v159
	v_add_f32_e32 v220, v158, v220
	s_waitcnt lgkmcnt(6)
	v_mfma_f32_32x32x16_bf16 v[50:65], v[194:197], v[146:149], v[50:65]
	v_exp_f32_e32 v160, v160
	v_add_f32_e32 v220, v159, v220
	v_exp_f32_e32 v161, v161
	v_add_f32_e32 v220, v160, v220
	v_cvt_pk_bf16_f32 v150, v154, v155
	s_waitcnt lgkmcnt(4)
	v_mfma_f32_32x32x16_bf16 v[34:49], v[198:201], v[146:149], v[34:49]
	v_add_f32_e32 v220, v161, v220
	v_cvt_pk_bf16_f32 v151, v156, v157
	v_cvt_pk_bf16_f32 v152, v158, v159
	v_cvt_pk_bf16_f32 v153, v160, v161
	v_add_f32_e32 v209, v209, v220
	ds_read_b64_tr_b16 v[154:155], v219 offset:17536
	ds_read_b64_tr_b16 v[156:157], v219 offset:20096
	ds_read_b64_tr_b16 v[158:159], v219 offset:17600
	ds_read_b64_tr_b16 v[160:161], v219 offset:20160
	s_waitcnt lgkmcnt(6)
	v_mfma_f32_32x32x16_bf16 v[114:129], v[202:205], v[150:153], v[114:129]
	v_exp_f32_e32 v130, v130
	v_exp_f32_e32 v131, v131
	v_exp_f32_e32 v132, v132
	v_add_f32_e32 v213, v130, v131
	v_exp_f32_e32 v133, v133
	s_waitcnt lgkmcnt(4)
	v_mfma_f32_32x32x16_bf16 v[82:97], v[214:217], v[150:153], v[82:97]
	v_add_f32_e32 v213, v132, v213
	v_exp_f32_e32 v134, v134
	v_add_f32_e32 v213, v133, v213
	v_exp_f32_e32 v135, v135
	v_add_f32_e32 v213, v134, v213
	s_waitcnt lgkmcnt(2)
	v_mfma_f32_32x32x16_bf16 v[50:65], v[154:157], v[150:153], v[50:65]
	v_exp_f32_e32 v136, v136
	v_add_f32_e32 v213, v135, v213
	v_exp_f32_e32 v137, v137
	v_add_f32_e32 v213, v136, v213
	v_cvt_pk_bf16_f32 v130, v130, v131
	s_waitcnt lgkmcnt(0)
	v_mfma_f32_32x32x16_bf16 v[34:49], v[158:161], v[150:153], v[34:49]
	v_add_f32_e32 v213, v137, v213
	v_cvt_pk_bf16_f32 v131, v132, v133
	v_cvt_pk_bf16_f32 v132, v134, v135
	v_cvt_pk_bf16_f32 v133, v136, v137
	s_nop 1
	v_mfma_f32_32x32x16_bf16 v[98:113], v[244:247], v[130:133], v[98:113]
	v_exp_f32_e32 v138, v138
	v_exp_f32_e32 v139, v139
	v_add_f32_e32 v213, v138, v213
	v_exp_f32_e32 v140, v140
	v_add_f32_e32 v213, v139, v213
	v_exp_f32_e32 v141, v141
	v_mfma_f32_32x32x16_bf16 v[66:81], v[248:251], v[130:133], v[66:81]
	v_add_f32_e32 v213, v140, v213
	v_exp_f32_e32 v142, v142
	v_add_f32_e32 v213, v141, v213
	v_exp_f32_e32 v143, v143
	v_add_f32_e32 v213, v142, v213
	v_mfma_f32_32x32x16_bf16 v[18:33], v[194:197], v[130:133], v[18:33]
	v_exp_f32_e32 v144, v144
	v_add_f32_e32 v213, v143, v213
	v_exp_f32_e32 v145, v145
	v_add_f32_e32 v213, v144, v213
	v_cvt_pk_bf16_f32 v134, v138, v139
	v_mfma_f32_32x32x16_bf16 v[2:17], v[198:201], v[130:133], v[2:17]
	v_add_f32_e32 v213, v145, v213
	v_cvt_pk_bf16_f32 v135, v140, v141
	v_cvt_pk_bf16_f32 v136, v142, v143
	v_cvt_pk_bf16_f32 v137, v144, v145
	v_add_f32_e32 v208, v208, v213
	s_nop 1
	v_mfma_f32_32x32x16_bf16 v[98:113], v[202:205], v[134:137], v[98:113]
	v_mfma_f32_32x32x16_bf16 v[66:81], v[214:217], v[134:137], v[66:81]
	v_mfma_f32_32x32x16_bf16 v[18:33], v[154:157], v[134:137], v[18:33]
	v_mfma_f32_32x32x16_bf16 v[2:17], v[158:161], v[134:137], v[2:17]
; #define ATT_LOADK(jt) do { _Pragma("unroll") for (int i_ = 0; i_ < NC; ++i_) { const int key_ = tid >> 3, dch_ = (tid & 7) + 8 * i_; \
;             const bf16_t* rp_ = P + (size_t)(tok0 + (jt) * 64 + key_) * PP + dch_ * 8; kreg[i_] = *(const u32x4*)(rp_ + kcol); } \
;         if (MODE == 2 && w == 0) cfreg = p.misc[(size_t)(tok0 + (jt) * 64 + lane) * MISCP + 64 + h]; } while (0)
; #define ATT_LOADV(jt) do { _Pragma("unroll") for (int i_ = 0; i_ < NC; ++i_) { const int key_ = tid >> 3, dch_ = (tid & 7) + 8 * i_; \
;             const bf16_t* rp_ = P + (size_t)(tok0 + (jt) * 64 + key_) * PP + dch_ * 8; vreg[i_] = *(const u32x4*)(rp_ + vcol); } } while (0)
; template <int MODE>
; __device__ __forceinline__ void attn_item(const AttnP& p, int b, int h, int qb, LAS unsigned char* lds) {
;     ...
;     for (int it = 0; it <= jt_max; ++it) {
;         const int jt = jt_max - it, k0 = jt * 64, buf = it & 1;
;         const bool has_next = it < jt_max;
;         if (has_next) { ATT_LOADK(jt - 1); ATT_LOADV(jt - 1); }
.Lsb_end:
	s_andn2_b64 vcc, exec, s[6:7]
	s_cbranch_vccnz .LBB0_495
.LBB0_575:
	s_waitcnt vmcnt(0) lgkmcnt(0)
	v_and_b32_e32 v135, 0xffff0000, v181
	v_and_b32_e32 v133, 0xffff0000, v180
	v_lshlrev_b32_e32 v134, 16, v181
	v_lshlrev_b32_e32 v132, 16, v180
	v_mov_b32_e32 v136, v135
	v_mov_b32_e32 v137, v133
	v_mov_b32_e32 v130, v134
	v_mov_b32_e32 v131, v132
	v_pk_mul_f32 v[136:137], v[136:137], v[136:137]
	v_and_b32_e32 v139, 0xffff0000, v178
	v_pk_fma_f32 v[130:131], v[130:131], v[130:131], v[136:137]
	v_and_b32_e32 v137, 0xffff0000, v179
	v_lshlrev_b32_e32 v136, 16, v179
	v_lshlrev_b32_e32 v138, 16, v178
	v_mov_b32_e32 v142, v139
	v_mov_b32_e32 v143, v137
	v_mov_b32_e32 v140, v138
	v_mov_b32_e32 v141, v136
	v_pk_mul_f32 v[142:143], v[142:143], v[142:143]
	s_xor_b32 s2, s5, 1
	v_pk_fma_f32 v[140:141], v[140:141], v[140:141], v[142:143]
	s_mul_i32 s2, s2, 0x9500
	v_add_f32_e32 v140, v140, v141
	v_add_f32_e32 v131, v131, v140
	v_add_f32_e32 v130, v130, v131
	s_add_i32 s2, s2, 0
	s_nop 0
	v_add_f32_dpp v130, v130, v130 quad_perm:[1,0,3,2] row_mask:0xf bank_mask:0xf bound_ctrl:1
	s_nop 1
	v_add_f32_dpp v130, v130, v130 quad_perm:[2,3,0,1] row_mask:0xf bank_mask:0xf bound_ctrl:1
	s_nop 1
	v_add_f32_dpp v130, v130, v130 row_half_mirror row_mask:0xf bank_mask:0xf bound_ctrl:1
	v_fmamk_f32 v130, v130, 0x3c800000, v211
	v_rsq_f32_e32 v140, v130
	s_nop 0
	v_pk_mul_f32 v[130:131], v[140:141], v[138:139] op_sel_hi:[0,1]
	v_pk_mul_f32 v[136:137], v[140:141], v[136:137] op_sel_hi:[0,1]
	v_pk_mul_f32 v[132:133], v[140:141], v[132:133] op_sel_hi:[0,1]
	v_pk_mul_f32 v[134:135], v[140:141], v[134:135] op_sel_hi:[0,1]
	v_cvt_pk_bf16_f32 v130, v130, v131
	v_cvt_pk_bf16_f32 v131, v136, v137
	v_cvt_pk_bf16_f32 v132, v132, v133
	v_cvt_pk_bf16_f32 v133, v134, v135
	v_add_u32_e32 v134, s2, v231
	ds_write_b128 v134, v[130:133]
	v_and_b32_e32 v135, 0xffff0000, v185
	v_and_b32_e32 v133, 0xffff0000, v184
	v_add_u32_e32 v130, s2, v232
	v_lshlrev_b32_e32 v134, 16, v185
	v_lshlrev_b32_e32 v132, 16, v184
	v_mov_b32_e32 v136, v135
	v_mov_b32_e32 v137, v133
	ds_write_b128 v130, v[186:189] offset:17408
	v_mov_b32_e32 v130, v134
	v_mov_b32_e32 v131, v132
	v_pk_mul_f32 v[136:137], v[136:137], v[136:137]
	v_and_b32_e32 v139, 0xffff0000, v182
	v_pk_fma_f32 v[130:131], v[130:131], v[130:131], v[136:137]
	v_and_b32_e32 v137, 0xffff0000, v183
	v_lshlrev_b32_e32 v136, 16, v183
	v_lshlrev_b32_e32 v138, 16, v182
	v_mov_b32_e32 v142, v139
	v_mov_b32_e32 v143, v137
	v_mov_b32_e32 v140, v138
	v_mov_b32_e32 v141, v136
	v_pk_mul_f32 v[142:143], v[142:143], v[142:143]
	s_nop 0
	v_pk_fma_f32 v[140:141], v[140:141], v[140:141], v[142:143]
	s_nop 0
	v_add_f32_e32 v140, v140, v141
	v_add_f32_e32 v131, v131, v140
	v_add_f32_e32 v130, v130, v131
	s_nop 1
	v_add_f32_dpp v130, v130, v130 quad_perm:[1,0,3,2] row_mask:0xf bank_mask:0xf bound_ctrl:1
	s_nop 1
	v_add_f32_dpp v130, v130, v130 quad_perm:[2,3,0,1] row_mask:0xf bank_mask:0xf bound_ctrl:1
	s_nop 1
	v_add_f32_dpp v130, v130, v130 row_half_mirror row_mask:0xf bank_mask:0xf bound_ctrl:1
	v_fmamk_f32 v130, v130, 0x3c800000, v211
	v_rsq_f32_e32 v140, v130
	s_nop 0
	v_pk_mul_f32 v[130:131], v[140:141], v[138:139] op_sel_hi:[0,1]
	v_pk_mul_f32 v[136:137], v[140:141], v[136:137] op_sel_hi:[0,1]
	v_pk_mul_f32 v[132:133], v[140:141], v[132:133] op_sel_hi:[0,1]
	v_pk_mul_f32 v[134:135], v[140:141], v[134:135] op_sel_hi:[0,1]
	v_cvt_pk_bf16_f32 v130, v130, v131
	v_cvt_pk_bf16_f32 v131, v136, v137
	v_cvt_pk_bf16_f32 v132, v132, v133
	v_cvt_pk_bf16_f32 v133, v134, v135
	v_add_u32_e32 v134, s2, v233
	ds_write_b128 v134, v[130:133]
	v_add_u32_e32 v130, s2, v234
	ds_write_b128 v130, v[190:193] offset:17408
	s_branch .LBB0_495
